# layer-1 out/ffn/ple-gate weight conversions (mats 11,13,15,17) moved from the HBM-bound prologue into the scan phase's staging-wave slices together with layer 2's (22-26); tails: R1 <- 27, L1 GU <- 28
# speedup vs baseline: 1.0193x; 1.0098x over previous
; __device__ __forceinline__ void convert_mats(Frame& F, int m_lo, int m_hi, int gw, int NGW) {
;     ...
;     for (int mi = m_lo; mi < m_hi; ++mi) {
.Lpro_skip:
	s_add_i32 s33, s33, 1
	s_branch .LBB0_14

; __device__ __forceinline__ void convert_mats(Frame& F, int m_lo, int m_hi, int gw, int NGW) {
;     ...
;     for (int mi = m_lo; mi < m_hi; ++mi) {
;         const MatI mt = kMats[mi]; const int cnt = (mt.Kp / 64) * (mt.Np / 64);
;         const float* src = in_ptr(F, mt.in_idx) + mt.src_off; const float* gain = mt.gain_idx >= 0 ? in_ptr(F, mt.gain_idx) + mt.gain_off : nullptr; bf16* dst = (bf16*)((unsigned char*)in_ptr(F, T_WS) + mt.dst_off);
.LBB0_14:
	s_lshl_b32 s4, 1, s33
	s_and_b32 s4, s4, 0x2a800
	s_cmp_lg_u32 s4, 0
	s_cbranch_scc1 .Lpro_skip
	s_mul_i32 s8, s33, 56
	s_getpc_b64 s[0:1]
	s_add_u32 s0, s0, _ZL5kMats@rel32@lo+4
	s_addc_u32 s1, s1, _ZL5kMats@rel32@hi+12
	s_mul_hi_u32 s9, s33, 56
	s_add_u32 s10, s0, s8
	s_addc_u32 s11, s1, s9
	s_getpc_b64 s[0:1]
	s_add_u32 s0, s0, _ZL5kMats@rel32@lo+12
	s_addc_u32 s1, s1, _ZL5kMats@rel32@hi+20
	s_add_u32 s0, s0, s8
	s_addc_u32 s1, s1, s9
	s_load_dword s12, s[10:11], 0x0
	s_getpc_b64 s[4:5]
	s_add_u32 s4, s4, _ZL5kMats@rel32@lo+28
	s_addc_u32 s5, s5, _ZL5kMats@rel32@hi+36
	s_add_u32 s6, s4, s8
	s_addc_u32 s7, s5, s9
	s_getpc_b64 s[4:5]
	s_add_u32 s4, s4, _ZL5kMats@rel32@lo+36
	s_addc_u32 s5, s5, _ZL5kMats@rel32@hi+44
	s_add_u32 s8, s4, s8
	s_addc_u32 s9, s5, s9
	s_waitcnt lgkmcnt(0)
	s_lshl_b32 s4, s12, 3
	s_add_i32 s4, s4, 0
	s_add_i32 s4, s4, 0x20400
	v_mov_b32_e32 v1, s4
	ds_read_b64 v[2:3], v1
	s_lshl_b64 s[4:5], 1, s33
	s_and_b32 s48, s4, 0xad433001
	s_cmp_eq_u64 s[48:49], 0
	s_mov_b64 s[50:51], 0
	s_waitcnt lgkmcnt(0)
	v_readfirstlane_b32 s12, v2
	v_readfirstlane_b32 s13, v3
	s_cbranch_scc1 .LBB0_16
	s_load_dwordx2 s[10:11], s[10:11], 0x10
	s_waitcnt lgkmcnt(0)
	s_lshl_b32 s5, s10, 3
	s_add_i32 s5, s5, 0
	s_add_i32 s5, s5, 0x20400
	v_mov_b32_e32 v1, s5
	ds_read_b64 v[2:3], v1
	s_ashr_i32 s15, s11, 31
	s_mov_b32 s14, s11
	s_lshl_b64 s[10:11], s[14:15], 2
	s_waitcnt lgkmcnt(0)
	v_readfirstlane_b32 s5, v2
	v_readfirstlane_b32 s16, v3
	s_add_u32 s50, s5, s10
	s_addc_u32 s51, s16, s11

;     __device__ __forceinline__ void ids() { lane = fresh_lane(); tid = wave * 64 + lane; }
; template <int L> __device__ __forceinline__ void layer_phases(Frame& F, const int lo, const int hi, const XcdBarrier& bar, const int bid) {
;     ...
;             {
;                 const int rem = (M / 256) * (6912 / 256) % F.G, nidle = rem ? F.G - rem : 0, ci = bid - rem;
;                 F.ids();
;                 if (nidle > 0) { if (ci >= 0) convert_mats(F, 22, 27, ci * NWAVES + F.wave, nidle * NWAVES); }
;                 else convert_mats(F, 22, 27, bid * NWAVES + F.wave, F.G * NWAVES);
;             }
.LBB0_1332:
	s_and_b64 vcc, exec, s[0:1]
	s_cbranch_vccz .LBB0_1449
	s_sub_i32 s0, s2, s33
	s_cmp_lt_i32 s0, 0
	s_mov_b32 s39, 0
	s_cbranch_scc1 .LBB0_1449
	s_lshl_b32 s0, s0, 3
	v_lshlrev_b32_e32 v0, 2, v141
	s_add_i32 s20, s0, s80
	s_lshl_b32 s0, s80, 14
	v_ashrrev_i32_e32 v143, 3, v141
	v_and_b32_e32 v145, 28, v0
	v_and_b32_e32 v0, 7, v141
	s_add_i32 s0, s0, 0
	v_mul_u32_u24_e32 v3, 0x420, v0
	v_lshlrev_b32_e32 v4, 2, v143
	v_lshl_add_u32 v1, v0, 4, s0
	v_add3_u32 v141, s0, v3, v4
	s_movk_i32 s0, 0x84
	v_lshlrev_b32_e32 v2, 3, v0
	v_mul_lo_u32 v3, v143, s0
	s_lshl_b32 s3, s3, 3
	v_mov_b32_e32 v0, 0
	v_add_u32_e32 v147, 8, v143
	v_add_u32_e32 v149, 16, v143
	v_add_u32_e32 v151, 24, v143
	s_mov_b32 s33, 27
	s_add_i32 s34, 0, 0x20520
	v_lshlrev_b32_e32 v132, 1, v2
	v_add_u32_e32 v152, v1, v3
	s_mov_b32 s35, 0
	s_branch .LBB0_1336
.LBB0_1335:
	s_add_i32 s33, s33, 1
	s_cmp_eq_u32 s33, 28
	s_mov_b32 s35, s43
	s_cbranch_scc1 .LBB0_1449

; __device__ __forceinline__ void convert_mats(Frame& F, int m_lo, int m_hi, int gw, int NGW) {
;     ...
;     for (int mi = m_lo; mi < m_hi; ++mi) {
;         const MatI mt = kMats[mi]; const int cnt = (mt.Kp / 64) * (mt.Np / 64);
;         const float* src = in_ptr(F, mt.in_idx) + mt.src_off; const float* gain = mt.gain_idx >= 0 ? in_ptr(F, mt.gain_idx) + mt.gain_off : nullptr; bf16* dst = (bf16*)((unsigned char*)in_ptr(F, T_WS) + mt.dst_off);
.Lcsa_find:
	s_cmp_lt_u32 s67, 9
	s_cbranch_scc1 .Lcsa_setup
	s_mov_b32 s69, 0
	s_branch .Lcsa_end
.Lcsa_setup:
	s_cmp_lg_u32 s67, 0
	s_cbranch_scc1 .Lcsa_m1
	s_mov_b32 s82, 32
	s_mov_b32 s83, 0x8000000
	s_mov_b32 s84, 0x2000
	s_mov_b32 s85, 0x1000
	s_mov_b32 s86, 0
	s_mov_b32 s87, 1024
	s_mov_b32 s88, 0x0
	s_mov_b32 s90, 0xbf00000
	s_mov_b32 s93, 0x204a8
	s_mov_b32 s94, 0
	s_branch .Lcsa_have
.Lcsa_m1:
	s_cmp_lg_u32 s67, 1
	s_cbranch_scc1 .Lcsa_m2
	s_mov_b32 s82, 176
	s_mov_b32 s83, 0x1745d18
	s_mov_b32 s84, 0xb000
	s_mov_b32 s85, 0x1000
	s_mov_b32 s86, 5632
	s_mov_b32 s87, 5632
	s_mov_b32 s88, 0x5800000
	s_mov_b32 s90, 0x11300000
	s_mov_b32 s93, 0x204d8
	s_mov_b32 s89, 0x2000
	s_mov_b32 s94, 0x204d0
	s_branch .Lcsa_have
.Lcsa_m2:
	s_cmp_lg_u32 s67, 2
	s_cbranch_scc1 .Lcsa_m3
	s_mov_b32 s82, 32
	s_mov_b32 s83, 0x8000000
	s_mov_b32 s84, 0x2000
	s_mov_b32 s85, 0x2c00
	s_mov_b32 s86, 0
	s_mov_b32 s87, 2816
	s_mov_b32 s88, 0x2c00000
	s_mov_b32 s90, 0x1ad00000
	s_mov_b32 s93, 0x204f0
	s_mov_b32 s94, 0
	s_branch .Lcsa_have
.Lcsa_m3:
	s_cmp_lg_u32 s67, 3
	s_cbranch_scc1 .Lcsa_m4
	s_mov_b32 s82, 32
	s_mov_b32 s83, 0x8000000
	s_mov_b32 s84, 0x2000
	s_mov_b32 s85, 0x1000
	s_mov_b32 s86, 0
	s_mov_b32 s87, 1024
	s_mov_b32 s88, 0x1000000
	s_mov_b32 s90, 0x1f700000
	s_mov_b32 s93, 0x20508
	s_mov_b32 s89, 0x2000
	s_mov_b32 s94, 0x20500
	s_branch .Lcsa_have
.Lcsa_m4:
	s_cmp_lg_u32 s67, 4
	s_cbranch_scc1 .Lcsa_m5
	s_mov_b32 s82, 96
	s_mov_b32 s83, 0x2aaaaab
	s_mov_b32 s84, 0x6000
	s_mov_b32 s85, 0x1000
	s_mov_b32 s86, 0
	s_mov_b32 s87, 3072
	s_mov_b32 s88, 0x0
	s_mov_b32 s90, 0xc700000
	s_mov_b32 s93, 0x204b8
	s_mov_b32 s89, 0x0
	s_mov_b32 s94, 0x204b0
	s_branch .Lcsa_have
.Lcsa_m5:
	s_cmp_lg_u32 s67, 5
	s_cbranch_scc1 .Lcsa_m6
	s_mov_b32 s82, 32
	s_mov_b32 s83, 0x8000000
	s_mov_b32 s84, 0x2000
	s_mov_b32 s85, 0x1000
	s_mov_b32 s86, 0
	s_mov_b32 s87, 1024
	s_mov_b32 s88, 0x0
	s_mov_b32 s90, 0xdf00000
	s_mov_b32 s93, 0x204c8
	s_mov_b32 s94, 0
	s_branch .Lcsa_have
.Lcsa_m6:
	s_cmp_lg_u32 s67, 6
	s_cbranch_scc1 .Lcsa_m7
	s_mov_b32 s82, 176
	s_mov_b32 s83, 0x1745d18
	s_mov_b32 s84, 0xb000
	s_mov_b32 s85, 0x1000
	s_mov_b32 s86, 5632
	s_mov_b32 s87, 5632
	s_mov_b32 s88, 0xb000000
	s_mov_b32 s90, 0x13f00000
	s_mov_b32 s93, 0x204d8
	s_mov_b32 s89, 0x4000
	s_mov_b32 s94, 0x204d0
	s_branch .Lcsa_have
.Lcsa_m7:
	s_cmp_lg_u32 s67, 7
	s_cbranch_scc1 .Lcsa_m8
	s_mov_b32 s82, 32
	s_mov_b32 s83, 0x8000000
	s_mov_b32 s84, 0x2000
	s_mov_b32 s85, 0x2c00
	s_mov_b32 s86, 0
	s_mov_b32 s87, 2816
	s_mov_b32 s88, 0x5800000
	s_mov_b32 s90, 0x1c300000
	s_mov_b32 s93, 0x204f0
	s_mov_b32 s94, 0
	s_branch .Lcsa_have
.Lcsa_m8:
	s_mov_b32 s82, 32
	s_mov_b32 s83, 0x8000000
	s_mov_b32 s84, 0x2000
	s_mov_b32 s85, 0x1000
	s_mov_b32 s86, 0
	s_mov_b32 s87, 1024
	s_mov_b32 s88, 0x2000000
	s_mov_b32 s90, 0x1ff00000
	s_mov_b32 s93, 0x20508
	s_mov_b32 s89, 0x4000
	s_mov_b32 s94, 0x20500

;     __device__ __forceinline__ void ids() { lane = fresh_lane(); tid = wave * 64 + lane; }
; #define ws ((unsigned char*)in_ptr(F, T_WS))
; template <int L> __device__ __forceinline__ void layer_phases(Frame& F, const int lo, const int hi, const XcdBarrier& bar, const int bid) {
;     ...
;         {
;             const int rem = (M / 256) * (2 * FF / 256) % F.G, nidle = rem ? F.G - rem : 0, ci = bid - rem;
;             if (nidle > 0 && ci >= 0) {
;                 if constexpr (L == 0) {
;                     pg8::Gemm g2{(const bf16*)(ws + WS_PB), (const bf16*)(ws + WS_WPP), M, 4 * D, PLE, (size_t)M * PLE * 2, 8, 1 << 30};
;                     pg8::StaticOrder S2; S2.init(M, 4 * D, nidle, ci);
;                     pg8::EpiScaleBf16<false> E2{(bf16*)(ws + WS_PPO), D, nullptr, D, (size_t)M * D, nullptr};
;                     pg8::gemm_phase<pg8::EpiScaleBf16<false>, pg8::StaticOrder, false, true>(F.lds, g2, S2, E2, F.wave);
;                 } else if constexpr (L == 1) { F.ids(); convert_mats(F, 27, 29, ci * NWAVES + F.wave, nidle * NWAVES); }
;                 else if constexpr (L == 2) { F.ids(); convert_mats(F, 29, 32, ci * NWAVES + F.wave, nidle * NWAVES); }
;             } else if (nidle == 0) {
;                 if constexpr (L == 0) {
;                     pg8::Gemm g2{(const bf16*)(ws + WS_PB), (const bf16*)(ws + WS_WPP), M, 4 * D, PLE, (size_t)M * PLE * 2, 8, 1 << 30};
;                     pg8::StaticOrder S2; S2.init(M, 4 * D, F.G, bid);
;                     pg8::EpiScaleBf16<false> E2{(bf16*)(ws + WS_PPO), D, nullptr, D, (size_t)M * D, nullptr};
;                     pg8::gemm_phase<pg8::EpiScaleBf16<false>, pg8::StaticOrder, false, true>(F.lds, g2, S2, E2, F.wave);
;                 } else if constexpr (L == 1) { F.ids(); convert_mats(F, 27, 29, bid * NWAVES + F.wave, F.G * NWAVES); }
;                 else if constexpr (L == 2) { F.ids(); convert_mats(F, 29, 32, bid * NWAVES + F.wave, F.G * NWAVES); }
;             }
.LBB0_2066:
	s_andn2_b64 vcc, exec, s[0:1]
	s_cbranch_vccnz .LBB0_2182
	v_mbcnt_lo_u32_b32 v0, -1, 0
	v_mbcnt_hi_u32_b32 v0, -1, v0
	s_lshl_b32 s0, s33, 3
	s_add_i32 s20, s0, s80
	s_lshl_b32 s0, s80, 14
	v_ashrrev_i32_e32 v141, 3, v0
	v_lshlrev_b32_e32 v1, 2, v0
	v_and_b32_e32 v0, 7, v0
	s_add_i32 s0, s0, 0
	v_mul_u32_u24_e32 v3, 0x420, v0
	s_waitcnt lgkmcnt(6)
	v_lshlrev_b32_e32 v4, 2, v141
	v_and_b32_e32 v143, 28, v1
	v_lshl_add_u32 v1, v0, 4, s0
	v_add3_u32 v145, s0, v3, v4
	s_movk_i32 s0, 0x84
	v_lshlrev_b32_e32 v2, 3, v0
	v_mul_lo_u32 v3, v141, s0
	s_lshl_b32 s3, s3, 3
	s_mov_b32 s39, 0
	v_mov_b32_e32 v0, 0
	v_add_u32_e32 v147, 8, v141
	v_add_u32_e32 v149, 16, v141
	v_add_u32_e32 v151, 24, v141
	s_mov_b64 s[0:1], 28
	s_mov_b64 s[44:45], 0
	s_add_i32 s33, 0, 0x20520
	v_lshlrev_b32_e32 v132, 1, v2
	v_add_u32_e32 v152, v1, v3
	s_mov_b32 s34, 0
	s_branch .LBB0_2069
.LBB0_2068:
	s_mov_b64 s[0:1], 29
	s_and_b64 vcc, exec, s[44:45]
	s_mov_b32 s34, s35
	s_mov_b64 s[44:45], -1
	s_cbranch_vccnz .LBB0_2182

;     __device__ __forceinline__ void ids() { lane = fresh_lane(); tid = wave * 64 + lane; }
; #define SEAM(k) do { } while (0)
; #define SEAM(k) do { if ((k) + 1 < hi) { XcdBarrier b_; b_.bar = (unsigned*)(ws + WS_CTL) + CW_BAR; b_.x = xb_xcc_id(); b_.st = (volatile LAS unsigned*)(F.lds + MISC_OFF) + 8; xcd_barrier(b_); } } while (0)
; #define ws ((unsigned char*)in_ptr(F, T_WS))
; template <int L> __device__ __forceinline__ void layer_phases(Frame& F, const int lo, const int hi, const XcdBarrier& bar, const int bid) {
;     ...
;         {
;             const int rem = (M / 256) * (2 * FF / 256) % F.G, nidle = rem ? F.G - rem : 0, ci = bid - rem;
;             if (nidle > 0 && ci >= 0) {
;                 if constexpr (L == 0) {
;                     pg8::Gemm g2{(const bf16*)(ws + WS_PB), (const bf16*)(ws + WS_WPP), M, 4 * D, PLE, (size_t)M * PLE * 2, 8, 1 << 30};
;                     pg8::StaticOrder S2; S2.init(M, 4 * D, nidle, ci);
;                     pg8::EpiScaleBf16<false> E2{(bf16*)(ws + WS_PPO), D, nullptr, D, (size_t)M * D, nullptr};
;                     pg8::gemm_phase<pg8::EpiScaleBf16<false>, pg8::StaticOrder, false, true>(F.lds, g2, S2, E2, F.wave);
;                 } else if constexpr (L == 1) { F.ids(); convert_mats(F, 27, 29, ci * NWAVES + F.wave, nidle * NWAVES); }
;                 else if constexpr (L == 2) { F.ids(); convert_mats(F, 29, 32, ci * NWAVES + F.wave, nidle * NWAVES); }
;             } else if (nidle == 0) {
;                 if constexpr (L == 0) {
;                     pg8::Gemm g2{(const bf16*)(ws + WS_PB), (const bf16*)(ws + WS_WPP), M, 4 * D, PLE, (size_t)M * PLE * 2, 8, 1 << 30};
;                     pg8::StaticOrder S2; S2.init(M, 4 * D, F.G, bid);
;                     pg8::EpiScaleBf16<false> E2{(bf16*)(ws + WS_PPO), D, nullptr, D, (size_t)M * D, nullptr};
;                     pg8::gemm_phase<pg8::EpiScaleBf16<false>, pg8::StaticOrder, false, true>(F.lds, g2, S2, E2, F.wave);
;                 } else if constexpr (L == 1) { F.ids(); convert_mats(F, 27, 29, bid * NWAVES + F.wave, F.G * NWAVES); }
;                 else if constexpr (L == 2) { F.ids(); convert_mats(F, 29, 32, bid * NWAVES + F.wave, F.G * NWAVES); }
;             }
;         }
;         SEAM(pb + 6);
.LBB0_2842:
	s_andn2_b64 vcc, exec, s[0:1]
	s_cbranch_vccnz .LBB0_2958
	v_mbcnt_lo_u32_b32 v0, -1, 0
	v_mbcnt_hi_u32_b32 v0, -1, v0
	s_lshl_b32 s0, s33, 3
	s_add_i32 s20, s0, s80
	s_lshl_b32 s0, s80, 14
	v_ashrrev_i32_e32 v141, 3, v0
	v_lshlrev_b32_e32 v1, 2, v0
	v_and_b32_e32 v0, 7, v0
	s_add_i32 s0, s0, 0
	v_mul_u32_u24_e32 v3, 0x420, v0
	s_waitcnt lgkmcnt(6)
	v_lshlrev_b32_e32 v4, 2, v141
	v_and_b32_e32 v143, 28, v1
	v_lshl_add_u32 v1, v0, 4, s0
	v_add3_u32 v145, s0, v3, v4
	s_movk_i32 s0, 0x84
	v_lshlrev_b32_e32 v2, 3, v0
	v_mul_lo_u32 v3, v141, s0
	s_lshl_b32 s3, s3, 3
	s_mov_b32 s39, 0
	v_mov_b32_e32 v0, 0
	v_add_u32_e32 v147, 8, v141
	v_add_u32_e32 v149, 16, v141
	v_add_u32_e32 v151, 24, v141
	s_mov_b32 s33, 30
	s_add_i32 s34, 0, 0x20520
	v_lshlrev_b32_e32 v132, 1, v2
	v_add_u32_e32 v152, v1, v3
	s_mov_b32 s35, 0
	s_branch .LBB0_2845
